# NSA sweeps: lazy online-softmax rescale (reference max raised only when a tile max exceeds it by >10 in log2 units), alpha exp and l/m moves only on the rescale path
# speedup vs baseline: 1.0097x; 1.0016x over previous
.LBB0_281:
	s_or_b64 exec, exec, s[4:5]
	s_waitcnt vmcnt(0)
	v_mul_f32_e32 v34, 0xbfb8aa3b, v116
	v_exp_f32_e32 v34, v34
	v_or_b32_e32 v0, v41, v43
	v_bitop3_b16 v0, v0, v47, v46 bitop3:0xfe
	v_bitop3_b16 v0, v0, v44, v42 bitop3:0xfe
	v_add_f32_e32 v34, 1.0, v34
	v_div_scale_f32 v35, s[4:5], v34, v34, 1.0
	v_rcp_f32_e32 v36, v35
	v_bitop3_b16 v0, v0, v40, v38 bitop3:0xfe
	v_lshlrev_b32_e32 v121, 2, v60
	v_add_u32_e32 v125, 0x10000, v121
	v_fma_f32 v37, -v35, v36, 1.0
	v_fmac_f32_e32 v36, v37, v36
	v_div_scale_f32 v37, vcc, 1.0, v34, 1.0
	v_mul_f32_e32 v39, v37, v36
	v_fma_f32 v41, -v35, v39, v37
	v_fmac_f32_e32 v39, v41, v36
	v_fma_f32 v35, -v35, v39, v37
	v_div_fmas_f32 v35, v35, v36, v39
	v_div_fixup_f32 v34, v35, v34, 1.0
	v_add_u32_e32 v35, 0x13280, v60
	ds_write_b8 v35, v0
	v_lshl_add_u32 v0, v61, 3, v205
	s_waitcnt lgkmcnt(0)
	s_barrier
	ds_read_b64 v[128:129], v0
	v_mul_f32_e32 v0, v34, v2
	v_mul_f32_e32 v3, v34, v3
	v_mul_f32_e32 v2, v34, v18
	ds_write2st64_b32 v121, v0, v3 offset0:144 offset1:148
	v_mul_f32_e32 v0, v34, v19
	ds_write2st64_b32 v121, v2, v0 offset0:208 offset1:212
	v_mul_f32_e32 v0, v34, v4
	v_mul_f32_e32 v3, v34, v5
	v_mul_f32_e32 v2, v34, v20
	ds_write2st64_b32 v121, v0, v3 offset0:152 offset1:156
	v_mul_f32_e32 v0, v34, v21
	ds_write2st64_b32 v121, v2, v0 offset0:216 offset1:220
	v_mul_f32_e32 v0, v34, v6
	v_mul_f32_e32 v3, v34, v7
	v_mul_f32_e32 v2, v34, v22
	ds_write2st64_b32 v121, v0, v3 offset0:160 offset1:164
	v_mul_f32_e32 v0, v34, v23
	ds_write2st64_b32 v121, v2, v0 offset0:224 offset1:228
	v_mul_f32_e32 v0, v34, v8
	v_mul_f32_e32 v3, v34, v9
	v_mul_f32_e32 v2, v34, v24
	ds_write2st64_b32 v121, v0, v3 offset0:168 offset1:172
	v_mul_f32_e32 v0, v34, v25
	ds_write2st64_b32 v121, v2, v0 offset0:232 offset1:236
	v_mul_f32_e32 v0, v34, v10
	v_mul_f32_e32 v3, v34, v11
	v_mul_f32_e32 v2, v34, v26
	ds_write2st64_b32 v121, v0, v3 offset0:176 offset1:180
	v_mul_f32_e32 v0, v34, v27
	ds_write2st64_b32 v121, v2, v0 offset0:240 offset1:244
	v_mul_f32_e32 v0, v34, v12
	v_mul_f32_e32 v3, v34, v13
	v_mul_f32_e32 v2, v34, v28
	ds_write2st64_b32 v121, v0, v3 offset0:184 offset1:188
	v_mul_f32_e32 v0, v34, v29
	ds_write2st64_b32 v121, v2, v0 offset0:248 offset1:252
	v_mul_f32_e32 v2, v34, v30
	v_mul_f32_e32 v0, v34, v14
	ds_write_b32 v125, v2
	v_mul_f32_e32 v2, v34, v15
	ds_write2st64_b32 v121, v0, v2 offset0:192 offset1:196
	v_mul_f32_e32 v0, v34, v31
	v_add_u32_e32 v127, 0x10400, v121
	v_mul_f32_e32 v2, v34, v32
	v_add_u32_e32 v135, 0x10800, v121
	ds_write_b32 v127, v0
	v_mul_f32_e32 v0, v34, v16
	ds_write_b32 v135, v2
	v_mul_f32_e32 v2, v34, v17
	s_or_b32 s11, s12, s11
	ds_write2st64_b32 v121, v0, v2 offset0:200 offset1:204
	v_mul_f32_e32 v0, v34, v33
	v_add_u32_e32 v152, 0x10c00, v121
	v_mov_b32_e32 v2, v133
	ds_write_b32 v152, v0
	s_lshl_b32 s6, s11, 19
	v_readlane_b32 s4, v253, 25
	s_add_u32 s4, s4, s6
	v_ashrrev_i32_e32 v158, 3, v2
	v_add_u32_e32 v0, 0x100, v2
	v_readlane_b32 s5, v253, 26
	v_ashrrev_i32_e32 v160, 3, v0
	v_ashrrev_i32_e32 v159, 31, v158
	v_lshlrev_b32_e32 v0, 3, v2
	s_addc_u32 s5, s5, 0
	v_readlane_b32 s7, v253, 27
	v_lshlrev_b64 v[4:5], 7, v[158:159]
	v_and_b32_e32 v20, 56, v0
	v_ashrrev_i32_e32 v161, 31, v160
	s_add_u32 s6, s7, s6
	v_readlane_b32 s7, v253, 28
	v_lshl_add_u64 v[4:5], s[4:5], 0, v[4:5]
	v_lshlrev_b32_e32 v0, 1, v20
	v_lshlrev_b64 v[8:9], 7, v[160:161]
	s_addc_u32 s7, s7, 0
	v_lshl_add_u64 v[4:5], v[4:5], 0, v[0:1]
	v_lshl_add_u64 v[8:9], s[4:5], 0, v[8:9]
	v_lshlrev_b64 v[12:13], 13, v[158:159]
	global_load_dwordx4 v[4:7], v[4:5], off
	v_lshl_add_u64 v[8:9], v[8:9], 0, v[0:1]
	v_lshl_add_u64 v[12:13], s[6:7], 0, v[12:13]
	v_lshlrev_b64 v[16:17], 13, v[160:161]
	global_load_dwordx4 v[8:11], v[8:9], off
	v_lshl_add_u64 v[162:163], v[12:13], 0, v[0:1]
	v_lshl_add_u64 v[16:17], s[6:7], 0, v[16:17]
	global_load_dwordx4 v[12:15], v[162:163], off
	v_lshl_add_u64 v[164:165], v[16:17], 0, v[0:1]
	global_load_dwordx4 v[16:19], v[164:165], off
	v_mad_u64_u32 v[166:167], s[6:7], v158, s21, v[20:21]
	v_lshlrev_b32_e32 v3, 1, v166
	v_mad_u64_u32 v[168:169], s[6:7], v160, s21, v[20:21]
	s_waitcnt lgkmcnt(0)
	s_barrier
	s_mov_b32 s12, 0
	s_cmp_lt_i32 s10, 0
	s_waitcnt vmcnt(3)
	ds_write_b128 v3, v[4:7]
	v_lshlrev_b32_e32 v4, 1, v168
	s_waitcnt vmcnt(2)
	ds_write_b128 v4, v[8:11]
	s_waitcnt vmcnt(1)
	ds_write_b128 v3, v[12:15] offset:9216
	s_waitcnt vmcnt(0)
	ds_write_b128 v4, v[16:19] offset:9216
	s_waitcnt lgkmcnt(0)
	s_barrier
	s_cbranch_scc1 .LBB0_298
	v_lshl_add_u64 v[170:171], s[4:5], 0, v[0:1]
	v_bfe_u32 v0, v2, 5, 1
	v_and_b32_e32 v116, 31, v2
	v_lshlrev_b32_e32 v131, 4, v0
	v_lshlrev_b32_e32 v2, 2, v0
	v_lshlrev_b32_e32 v0, 3, v0
	v_mov_b32_e32 v14, v1
	v_mov_b32_e32 v15, v1
	v_sub_u32_e32 v159, v126, v2
	v_sub_u32_e32 v161, 0, v0
	v_mov_b32_e32 v0, v1
	v_mov_b32_e32 v2, v1
	v_mov_b32_e32 v3, v1
	v_mov_b32_e32 v4, v1
	v_mov_b32_e32 v5, v1
	v_mov_b32_e32 v6, v1
	v_mov_b32_e32 v7, v1
	v_mov_b32_e32 v8, v1
	v_mov_b32_e32 v9, v1
	v_mov_b32_e32 v10, v1
	v_mov_b32_e32 v11, v1
	v_mov_b32_e32 v12, v1
	v_mov_b32_e32 v13, v1
	v_mov_b64_e32 v[30:31], v[14:15]
	v_mov_b64_e32 v[46:47], v[14:15]
	v_mul_u32_u24_e32 v156, 0x48, v116
	v_mov_b32_e32 v167, 0xf149f2ca
	v_mov_b32_e32 v169, 0
	v_mov_b64_e32 v[28:29], v[12:13]
	v_mov_b64_e32 v[26:27], v[10:11]
	v_mov_b64_e32 v[24:25], v[8:9]
	v_mov_b64_e32 v[22:23], v[6:7]
	v_mov_b64_e32 v[20:21], v[4:5]
	v_mov_b64_e32 v[18:19], v[2:3]
	v_mov_b64_e32 v[16:17], v[0:1]
	v_mov_b64_e32 v[44:45], v[12:13]
	v_mov_b64_e32 v[42:43], v[10:11]
	v_mov_b64_e32 v[40:41], v[8:9]
	v_mov_b64_e32 v[38:39], v[6:7]
	v_mov_b64_e32 v[36:37], v[4:5]
	v_mov_b64_e32 v[34:35], v[2:3]
	v_mov_b64_e32 v[32:33], v[0:1]
	v_lshrrev_b32_e32 v217, 1, v116
	v_xor_b32_e32 v217, v217, v116
	v_and_b32_e32 v217, 4, v217
	v_lshl_add_u32 v217, v217, 1, v217
	v_xor_b32_e32 v217, v217, v116
	s_movk_i32 s4, 0x80
	v_mad_u64_u32 v[190:191], vcc, v158, s4, v[170:171]
	s_mov_b64 s[6:7], 0x800
	v_lshl_add_u64 v[190:191], v[190:191], 0, s[6:7]
	v_mov_b32_e32 v219, v202
.LBB0_283:
	s_add_i32 s13, s12, 1
	s_min_i32 s4, s13, s10
	s_lshl_b32 s96, s4, 6
	s_lshl_b64 s[6:7], s[96:97], 7
	s_lshl_b64 s[4:5], s[96:97], 1
	v_lshl_add_u64 v[2:3], v[190:191], 0, s[6:7]
	global_load_dwordx4 v[8:11], v[2:3], off offset:-2048
	s_nop 0
	global_load_dwordx4 v[4:7], v[2:3], off offset:2048
	v_lshl_add_u64 v[2:3], v[162:163], 0, s[4:5]
	v_lshl_add_u64 v[48:49], v[164:165], 0, s[4:5]
	global_load_dwordx4 v[12:15], v[2:3], off
	global_load_dwordx4 v[112:115], v[48:49], off
	s_and_b32 s14, s12, 1
	s_mul_i32 s4, s14, 0x4800
	v_lshrrev_b64 v[2:3], s12, v[128:129]
	s_lshl_b32 s15, s12, 6
	v_and_b32_e32 v0, 1, v2
	s_or_b32 s5, s15, 63
	v_or_b32_e32 v3, s4, v131
	v_cmp_eq_u64_e64 s[38:39], 0, v[0:1]
	s_cmp_gt_i32 s5, s8
	v_add_u32_e32 v172, v3, v161
	s_mov_b64 s[4:5], -1
	s_cbranch_scc1 .LBB0_289
	v_mad_u32_u24 v0, v217, s37, v3
	v_lshl_add_u32 v215, v156, 1, v3
	ds_read_b128 v[220:223], v0
	ds_read_b128 v[236:239], v0 offset:4608
	ds_read_b128 v[224:227], v0 offset:32
	ds_read_b128 v[240:243], v0 offset:4640
	ds_read_b128 v[228:231], v0 offset:64
	ds_read_b128 v[244:247], v0 offset:4672
	ds_read_b128 v[232:235], v0 offset:96
	ds_read_b128 v[248:251], v0 offset:4704
	ds_read_b128 v[64:67], v215 offset:9216
	ds_read_b128 v[68:71], v215 offset:13824
	ds_read_b128 v[72:75], v215 offset:9248
	ds_read_b128 v[76:79], v215 offset:13856
	s_waitcnt lgkmcnt(11)
	v_mfma_f32_32x32x16_bf16 v[80:95], v[220:223], v[96:99], 0
	s_waitcnt lgkmcnt(10)
	v_mfma_f32_32x32x16_bf16 v[48:63], v[236:239], v[96:99], 0
	s_waitcnt lgkmcnt(9)
	v_mfma_f32_32x32x16_bf16 v[80:95], v[224:227], v[100:103], v[80:95]
	s_waitcnt lgkmcnt(8)
	v_mfma_f32_32x32x16_bf16 v[48:63], v[240:243], v[100:103], v[48:63]
	s_waitcnt lgkmcnt(7)
	v_mfma_f32_32x32x16_bf16 v[80:95], v[228:231], v[104:107], v[80:95]
	s_waitcnt lgkmcnt(6)
	v_mfma_f32_32x32x16_bf16 v[48:63], v[244:247], v[104:107], v[48:63]
	s_waitcnt lgkmcnt(5)
	v_mfma_f32_32x32x16_bf16 v[80:95], v[232:235], v[108:111], v[80:95]
	s_waitcnt lgkmcnt(4)
	v_mfma_f32_32x32x16_bf16 v[48:63], v[248:251], v[108:111], v[48:63]
	ds_read_b128 v[220:223], v215 offset:9280
	ds_read_b128 v[224:227], v215 offset:13888
	ds_read_b128 v[228:231], v215 offset:9312
	ds_read_b128 v[232:235], v215 offset:13920
	s_nop 7
	v_max3_f32 v0, v80, v81, v82
	v_max3_f32 v2, v88, v89, v90
	v_max3_f32 v0, v0, v83, v84
	v_max3_f32 v2, v2, v91, v92
	v_max3_f32 v0, v0, v85, v86
	v_max3_f32 v2, v2, v93, v94
	v_max3_f32 v0, v0, v87, v95
	v_max_f32_e32 v0, v0, v2
	v_cndmask_b32_e64 v0, v0, v202, s[38:39]
	ds_bpermute_b32 v2, v119, v0
	v_max3_f32 v175, v48, v49, v50
	v_max3_f32 v214, v56, v57, v58
	v_max3_f32 v175, v175, v51, v52
	v_max3_f32 v214, v214, v59, v60
	v_max3_f32 v175, v175, v53, v54
	v_max3_f32 v214, v214, v61, v62
	v_max3_f32 v175, v175, v55, v63
	v_max_f32_e32 v175, v175, v214
	v_cndmask_b32_e64 v175, v175, v202, s[38:39]
	ds_bpermute_b32 v214, v119, v175
	s_waitcnt lgkmcnt(1)
	v_max_f32_e32 v0, v0, v2
	v_cmp_gt_f32_e32 vcc, v0, v219
	s_cmp_eq_u64 vcc, 0
	s_cbranch_scc1 .Lnsw_keep0
	v_max_f32_e32 v173, v167, v0
	v_sub_f32_e32 v0, v167, v173
	v_exp_f32_e32 v0, v0
	v_mov_b32_e32 v167, v173
	v_add_f32_e32 v219, 0x41200000, v173
	v_mul_f32_e32 v169, v169, v0
	v_pk_mul_f32 v[46:47], v[46:47], v[0:1] op_sel_hi:[1,0]
	v_pk_mul_f32 v[44:45], v[44:45], v[0:1] op_sel_hi:[1,0]
	v_pk_mul_f32 v[42:43], v[42:43], v[0:1] op_sel_hi:[1,0]
	v_pk_mul_f32 v[40:41], v[40:41], v[0:1] op_sel_hi:[1,0]
	v_pk_mul_f32 v[38:39], v[38:39], v[0:1] op_sel_hi:[1,0]
	v_pk_mul_f32 v[36:37], v[36:37], v[0:1] op_sel_hi:[1,0]
	v_pk_mul_f32 v[34:35], v[34:35], v[0:1] op_sel_hi:[1,0]
	v_pk_mul_f32 v[32:33], v[32:33], v[0:1] op_sel_hi:[1,0]
	v_pk_mul_f32 v[30:31], v[30:31], v[0:1] op_sel_hi:[1,0]
	v_pk_mul_f32 v[28:29], v[28:29], v[0:1] op_sel_hi:[1,0]
	v_pk_mul_f32 v[26:27], v[26:27], v[0:1] op_sel_hi:[1,0]
	v_pk_mul_f32 v[24:25], v[24:25], v[0:1] op_sel_hi:[1,0]
	v_pk_mul_f32 v[22:23], v[22:23], v[0:1] op_sel_hi:[1,0]
	v_pk_mul_f32 v[20:21], v[20:21], v[0:1] op_sel_hi:[1,0]
	v_pk_mul_f32 v[18:19], v[18:19], v[0:1] op_sel_hi:[1,0]
	v_pk_mul_f32 v[16:17], v[16:17], v[0:1] op_sel_hi:[1,0]
.Lnsw_keep0:
	v_cndmask_b32_e64 v174, v167, v206, s[38:39]
	v_sub_f32_e32 v80, v80, v174
	v_exp_f32_e32 v80, v80
	v_sub_f32_e32 v81, v81, v174
	v_exp_f32_e32 v81, v81
	v_sub_f32_e32 v82, v82, v174
	v_exp_f32_e32 v82, v82
	v_add_f32_e32 v213, v81, v80
	v_sub_f32_e32 v83, v83, v174
	v_exp_f32_e32 v83, v83
	v_add_f32_e32 v213, v82, v213
	v_cvt_pk_bf16_f32 v176, v80, v81
	v_sub_f32_e32 v84, v84, v174
	v_exp_f32_e32 v84, v84
	v_add_f32_e32 v213, v83, v213
	v_sub_f32_e32 v85, v85, v174
	v_exp_f32_e32 v85, v85
	v_add_f32_e32 v213, v84, v213
	v_cvt_pk_bf16_f32 v177, v82, v83
	v_sub_f32_e32 v86, v86, v174
	v_exp_f32_e32 v86, v86
	v_add_f32_e32 v213, v85, v213
	v_sub_f32_e32 v87, v87, v174
	v_exp_f32_e32 v87, v87
	v_add_f32_e32 v213, v86, v213
	v_cvt_pk_bf16_f32 v178, v84, v85
	v_sub_f32_e32 v88, v88, v174
	v_exp_f32_e32 v88, v88
	v_add_f32_e32 v213, v87, v213
	v_sub_f32_e32 v89, v89, v174
	v_exp_f32_e32 v89, v89
	v_add_f32_e32 v213, v88, v213
	v_cvt_pk_bf16_f32 v179, v86, v87
	v_sub_f32_e32 v90, v90, v174
	v_exp_f32_e32 v90, v90
	v_add_f32_e32 v213, v89, v213
	v_mfma_f32_32x32x16_bf16 v[32:47], v[64:67], v[176:179], v[32:47]
	v_mfma_f32_32x32x16_bf16 v[16:31], v[68:71], v[176:179], v[16:31]
	v_sub_f32_e32 v91, v91, v174
	v_exp_f32_e32 v91, v91
	v_add_f32_e32 v213, v90, v213
	v_cvt_pk_bf16_f32 v180, v88, v89
	v_sub_f32_e32 v92, v92, v174
	v_exp_f32_e32 v92, v92
	v_add_f32_e32 v213, v91, v213
	v_sub_f32_e32 v93, v93, v174
	v_exp_f32_e32 v93, v93
	v_add_f32_e32 v213, v92, v213
	v_cvt_pk_bf16_f32 v181, v90, v91
	v_sub_f32_e32 v94, v94, v174
	v_exp_f32_e32 v94, v94
	v_add_f32_e32 v213, v93, v213
	v_sub_f32_e32 v95, v95, v174
	v_exp_f32_e32 v95, v95
	v_add_f32_e32 v213, v94, v213
	v_cvt_pk_bf16_f32 v182, v92, v93
	v_add_f32_e32 v213, v95, v213
	v_cvt_pk_bf16_f32 v183, v94, v95
	v_add_f32_e32 v169, v169, v213
	s_nop 0
	v_mfma_f32_32x32x16_bf16 v[32:47], v[72:75], v[180:183], v[32:47]
	v_mfma_f32_32x32x16_bf16 v[16:31], v[76:79], v[180:183], v[16:31]
	s_waitcnt lgkmcnt(0)
	v_max_f32_e32 v175, v175, v214
	v_cmp_gt_f32_e32 vcc, v175, v219
	s_cmp_eq_u64 vcc, 0
	s_cbranch_scc1 .Lnsw_keep1
	v_max_f32_e32 v173, v167, v175
	v_sub_f32_e32 v0, v167, v173
	v_exp_f32_e32 v0, v0
	v_mov_b32_e32 v167, v173
	v_add_f32_e32 v219, 0x41200000, v173
	v_mul_f32_e32 v169, v169, v0
	v_pk_mul_f32 v[46:47], v[46:47], v[0:1] op_sel_hi:[1,0]
	v_pk_mul_f32 v[44:45], v[44:45], v[0:1] op_sel_hi:[1,0]
	v_pk_mul_f32 v[42:43], v[42:43], v[0:1] op_sel_hi:[1,0]
	v_pk_mul_f32 v[40:41], v[40:41], v[0:1] op_sel_hi:[1,0]
	v_pk_mul_f32 v[38:39], v[38:39], v[0:1] op_sel_hi:[1,0]
	v_pk_mul_f32 v[36:37], v[36:37], v[0:1] op_sel_hi:[1,0]
	v_pk_mul_f32 v[34:35], v[34:35], v[0:1] op_sel_hi:[1,0]
	v_pk_mul_f32 v[32:33], v[32:33], v[0:1] op_sel_hi:[1,0]
	v_pk_mul_f32 v[30:31], v[30:31], v[0:1] op_sel_hi:[1,0]
	v_pk_mul_f32 v[28:29], v[28:29], v[0:1] op_sel_hi:[1,0]
	v_pk_mul_f32 v[26:27], v[26:27], v[0:1] op_sel_hi:[1,0]
	v_pk_mul_f32 v[24:25], v[24:25], v[0:1] op_sel_hi:[1,0]
	v_pk_mul_f32 v[22:23], v[22:23], v[0:1] op_sel_hi:[1,0]
	v_pk_mul_f32 v[20:21], v[20:21], v[0:1] op_sel_hi:[1,0]
	v_pk_mul_f32 v[18:19], v[18:19], v[0:1] op_sel_hi:[1,0]
	v_pk_mul_f32 v[16:17], v[16:17], v[0:1] op_sel_hi:[1,0]
.Lnsw_keep1:
	v_cndmask_b32_e64 v174, v167, v206, s[38:39]
	v_sub_f32_e32 v48, v48, v174
	v_exp_f32_e32 v48, v48
	v_sub_f32_e32 v49, v49, v174
	v_exp_f32_e32 v49, v49
	v_sub_f32_e32 v50, v50, v174
	v_exp_f32_e32 v50, v50
	v_add_f32_e32 v213, v49, v48
	v_sub_f32_e32 v51, v51, v174
	v_exp_f32_e32 v51, v51
	v_add_f32_e32 v213, v50, v213
	v_cvt_pk_bf16_f32 v80, v48, v49
	v_sub_f32_e32 v52, v52, v174
	v_exp_f32_e32 v52, v52
	v_add_f32_e32 v213, v51, v213
	v_sub_f32_e32 v53, v53, v174
	v_exp_f32_e32 v53, v53
	v_add_f32_e32 v213, v52, v213
	v_cvt_pk_bf16_f32 v81, v50, v51
	v_sub_f32_e32 v54, v54, v174
	v_exp_f32_e32 v54, v54
	v_add_f32_e32 v213, v53, v213
	v_sub_f32_e32 v55, v55, v174
	v_exp_f32_e32 v55, v55
	v_add_f32_e32 v213, v54, v213
	v_cvt_pk_bf16_f32 v82, v52, v53
	v_sub_f32_e32 v56, v56, v174
	v_exp_f32_e32 v56, v56
	v_add_f32_e32 v213, v55, v213
	v_sub_f32_e32 v57, v57, v174
	v_exp_f32_e32 v57, v57
	v_add_f32_e32 v213, v56, v213
	v_cvt_pk_bf16_f32 v83, v54, v55
	v_sub_f32_e32 v58, v58, v174
	v_exp_f32_e32 v58, v58
	v_add_f32_e32 v213, v57, v213
	v_mfma_f32_32x32x16_bf16 v[32:47], v[220:223], v[80:83], v[32:47]
	v_mfma_f32_32x32x16_bf16 v[16:31], v[224:227], v[80:83], v[16:31]
	v_sub_f32_e32 v59, v59, v174
	v_exp_f32_e32 v59, v59
	v_add_f32_e32 v213, v58, v213
	v_cvt_pk_bf16_f32 v84, v56, v57
	v_sub_f32_e32 v60, v60, v174
	v_exp_f32_e32 v60, v60
	v_add_f32_e32 v213, v59, v213
	v_sub_f32_e32 v61, v61, v174
	v_exp_f32_e32 v61, v61
	v_add_f32_e32 v213, v60, v213
	v_cvt_pk_bf16_f32 v85, v58, v59
	v_sub_f32_e32 v62, v62, v174
	v_exp_f32_e32 v62, v62
	v_add_f32_e32 v213, v61, v213
	v_sub_f32_e32 v63, v63, v174
	v_exp_f32_e32 v63, v63
	v_add_f32_e32 v213, v62, v213
	v_cvt_pk_bf16_f32 v86, v60, v61
	v_add_f32_e32 v213, v63, v213
	v_cvt_pk_bf16_f32 v87, v62, v63
	v_add_f32_e32 v169, v169, v213
	s_nop 0
	v_mfma_f32_32x32x16_bf16 v[32:47], v[228:231], v[84:87], v[32:47]
	v_mfma_f32_32x32x16_bf16 v[16:31], v[232:235], v[84:87], v[16:31]
	s_branch .LBB0_296

.LBB0_299:
	v_mul_f32_e32 v0, 0xbfb8aa3b, v117
	v_exp_f32_e32 v0, v0
	s_lshl_b32 s4, s11, 18
	s_sub_i32 s5, 0xde1, s9
	s_max_i32 s12, s5, 0
	v_add_f32_e32 v0, 1.0, v0
	v_div_scale_f32 v3, s[6:7], v0, v0, 1.0
	v_rcp_f32_e32 v4, v3
	v_readlane_b32 s5, v253, 30
	v_fma_f32 v5, -v3, v4, 1.0
	v_fmac_f32_e32 v4, v5, v4
	v_div_scale_f32 v5, vcc, 1.0, v0, 1.0
	v_mul_f32_e32 v6, v5, v4
	v_fma_f32 v7, -v3, v6, v5
	v_fmac_f32_e32 v6, v7, v4
	v_fma_f32 v3, -v3, v6, v5
	v_div_fmas_f32 v3, v3, v4, v6
	v_div_fixup_f32 v0, v3, v0, 1.0
	ds_bpermute_b32 v3, v119, v2
	s_waitcnt lgkmcnt(0)
	v_add_f32_e32 v2, v2, v3
	v_div_scale_f32 v3, s[6:7], v2, v2, v0
	v_rcp_f32_e32 v4, v3
	s_lshl_b32 s6, s4, 1
	v_readlane_b32 s4, v253, 29
	s_add_u32 s4, s4, s6
	v_fma_f32 v5, -v3, v4, 1.0
	v_fmac_f32_e32 v4, v5, v4
	v_div_scale_f32 v5, vcc, v0, v2, v0
	v_mul_f32_e32 v6, v5, v4
	v_fma_f32 v7, -v3, v6, v5
	v_fmac_f32_e32 v6, v7, v4
	v_fma_f32 v3, -v3, v6, v5
	v_div_fmas_f32 v3, v3, v4, v6
	v_div_fixup_f32 v0, v3, v2, v0
	ds_read2st64_b32 v[2:3], v121 offset0:144 offset1:148
	ds_read2st64_b32 v[4:5], v121 offset0:208 offset1:212
	s_addc_u32 s5, s5, 0
	v_readlane_b32 s7, v253, 31
	s_add_u32 s6, s7, s6
	s_waitcnt lgkmcnt(1)
	v_fma_f32 v2, v64, v0, v2
	v_fmac_f32_e32 v3, v65, v0
	ds_write2st64_b32 v121, v2, v3 offset0:144 offset1:148
	ds_read2st64_b32 v[2:3], v121 offset0:152 offset1:156
	s_waitcnt lgkmcnt(2)
	v_fma_f32 v4, v48, v0, v4
	v_fmac_f32_e32 v5, v49, v0
	ds_write2st64_b32 v121, v4, v5 offset0:208 offset1:212
	ds_read2st64_b32 v[4:5], v121 offset0:216 offset1:220
	s_waitcnt lgkmcnt(2)
	v_fma_f32 v2, v66, v0, v2
	v_fmac_f32_e32 v3, v67, v0
	ds_write2st64_b32 v121, v2, v3 offset0:152 offset1:156
	ds_read2st64_b32 v[2:3], v121 offset0:160 offset1:164
	s_waitcnt lgkmcnt(2)
	v_fma_f32 v4, v50, v0, v4
	v_fmac_f32_e32 v5, v51, v0
	ds_write2st64_b32 v121, v4, v5 offset0:216 offset1:220
	ds_read2st64_b32 v[4:5], v121 offset0:224 offset1:228
	s_waitcnt lgkmcnt(2)
	v_fma_f32 v2, v68, v0, v2
	v_fmac_f32_e32 v3, v69, v0
	ds_write2st64_b32 v121, v2, v3 offset0:160 offset1:164
	ds_read2st64_b32 v[2:3], v121 offset0:168 offset1:172
	s_waitcnt lgkmcnt(2)
	v_fma_f32 v4, v52, v0, v4
	v_fmac_f32_e32 v5, v53, v0
	ds_write2st64_b32 v121, v4, v5 offset0:224 offset1:228
	ds_read2st64_b32 v[4:5], v121 offset0:232 offset1:236
	s_waitcnt lgkmcnt(2)
	v_fma_f32 v2, v70, v0, v2
	v_fmac_f32_e32 v3, v71, v0
	ds_write2st64_b32 v121, v2, v3 offset0:168 offset1:172
	ds_read2st64_b32 v[2:3], v121 offset0:176 offset1:180
	s_waitcnt lgkmcnt(2)
	v_fma_f32 v4, v54, v0, v4
	v_fmac_f32_e32 v5, v55, v0
	ds_write2st64_b32 v121, v4, v5 offset0:232 offset1:236
	ds_read2st64_b32 v[4:5], v121 offset0:240 offset1:244
	s_waitcnt lgkmcnt(2)
	v_fma_f32 v2, v72, v0, v2
	v_fmac_f32_e32 v3, v73, v0
	ds_write2st64_b32 v121, v2, v3 offset0:176 offset1:180
	ds_read2st64_b32 v[2:3], v121 offset0:184 offset1:188
	s_waitcnt lgkmcnt(2)
	v_fma_f32 v4, v56, v0, v4
	v_fmac_f32_e32 v5, v57, v0
	ds_write2st64_b32 v121, v4, v5 offset0:240 offset1:244
	ds_read2st64_b32 v[4:5], v121 offset0:248 offset1:252
	s_waitcnt lgkmcnt(2)
	v_fma_f32 v2, v74, v0, v2
	v_fmac_f32_e32 v3, v75, v0
	ds_write2st64_b32 v121, v2, v3 offset0:184 offset1:188
	ds_read2st64_b32 v[2:3], v121 offset0:192 offset1:196
	s_waitcnt lgkmcnt(2)
	v_fma_f32 v4, v58, v0, v4
	v_fmac_f32_e32 v5, v59, v0
	ds_write2st64_b32 v121, v4, v5 offset0:248 offset1:252
	ds_read_b32 v4, v125
	s_waitcnt lgkmcnt(2)
	v_fma_f32 v2, v76, v0, v2
	v_fmac_f32_e32 v3, v77, v0
	ds_write2st64_b32 v121, v2, v3 offset0:192 offset1:196
	ds_read_b32 v2, v127
	s_waitcnt lgkmcnt(2)
	v_fmac_f32_e32 v4, v60, v0
	ds_write_b32 v125, v4
	ds_read_b32 v4, v135
	v_readlane_b32 s7, v253, 32
	s_waitcnt lgkmcnt(2)
	v_fmac_f32_e32 v2, v61, v0
	ds_write_b32 v127, v2
	ds_read2st64_b32 v[2:3], v121 offset0:200 offset1:204
	v_mov_b32_e32 v6, v133
	s_addc_u32 s7, s7, 0
	s_lshr_b32 s11, s12, 6
	s_and_b32 s12, s12, 0x3ffffc0
	s_waitcnt lgkmcnt(0)
	v_fma_f32 v2, v78, v0, v2
	v_fmac_f32_e32 v3, v79, v0
	ds_write2st64_b32 v121, v2, v3 offset0:200 offset1:204
	ds_read_b32 v2, v152
	v_fmac_f32_e32 v4, v62, v0
	ds_write_b32 v135, v4
	s_lshl_b32 s96, s12, 1
	s_cmp_gt_i32 s11, s10
	s_waitcnt lgkmcnt(1)
	v_fmac_f32_e32 v2, v63, v0
	ds_write_b32 v152, v2
	s_nop 0
	v_ashrrev_i32_e32 v116, 3, v6
	v_add_u32_e32 v0, 0x100, v6
	v_add_u32_e32 v2, s12, v116
	v_ashrrev_i32_e32 v128, 3, v0
	v_ashrrev_i32_e32 v3, 31, v2
	v_lshlrev_b32_e32 v0, 3, v6
	v_lshlrev_b64 v[2:3], 7, v[2:3]
	v_and_b32_e32 v24, 56, v0
	v_lshl_add_u64 v[2:3], s[4:5], 0, v[2:3]
	v_lshlrev_b32_e32 v0, 1, v24
	v_lshl_add_u64 v[2:3], v[2:3], 0, v[0:1]
	global_load_dwordx4 v[8:11], v[2:3], off
	v_add_u32_e32 v2, s12, v128
	v_ashrrev_i32_e32 v3, 31, v2
	v_lshlrev_b64 v[2:3], 7, v[2:3]
	v_lshl_add_u64 v[2:3], s[4:5], 0, v[2:3]
	v_lshl_add_u64 v[2:3], v[2:3], 0, v[0:1]
	v_ashrrev_i32_e32 v117, 31, v116
	global_load_dwordx4 v[12:15], v[2:3], off
	v_lshlrev_b64 v[2:3], 13, v[116:117]
	v_lshl_add_u64 v[2:3], s[6:7], 0, v[2:3]
	v_lshl_add_u64 v[4:5], v[2:3], 0, s[96:97]
	v_lshl_add_u64 v[4:5], v[4:5], 0, v[0:1]
	v_ashrrev_i32_e32 v129, 31, v128
	global_load_dwordx4 v[16:19], v[4:5], off
	v_lshlrev_b64 v[4:5], 13, v[128:129]
	v_lshl_add_u64 v[4:5], s[6:7], 0, v[4:5]
	v_lshl_add_u64 v[20:21], v[4:5], 0, s[96:97]
	v_lshl_add_u64 v[20:21], v[20:21], 0, v[0:1]
	global_load_dwordx4 v[20:23], v[20:21], off
	v_mad_u64_u32 v[158:159], s[6:7], v116, s21, v[24:25]
	v_lshlrev_b32_e32 v7, 1, v158
	v_mad_u64_u32 v[160:161], s[6:7], v128, s21, v[24:25]
	s_waitcnt lgkmcnt(0)
	s_barrier
	s_waitcnt vmcnt(3)
	ds_write_b128 v7, v[8:11]
	v_lshlrev_b32_e32 v8, 1, v160
	s_waitcnt vmcnt(2)
	ds_write_b128 v8, v[12:15]
	s_waitcnt vmcnt(1)
	ds_write_b128 v7, v[16:19] offset:9216
	s_waitcnt vmcnt(0)
	ds_write_b128 v8, v[20:23] offset:9216
	s_waitcnt lgkmcnt(0)
	s_barrier
	s_cbranch_scc1 .LBB0_316
	v_lshl_add_u64 v[162:163], s[4:5], 0, v[0:1]
	v_lshl_add_u64 v[164:165], v[2:3], 0, v[0:1]
	v_lshl_add_u64 v[166:167], v[4:5], 0, v[0:1]
	v_bfe_u32 v0, v6, 5, 1
	v_lshlrev_b32_e32 v129, 4, v0
	v_lshlrev_b32_e32 v131, 2, v0
	v_lshlrev_b32_e32 v0, 3, v0
	v_mov_b32_e32 v14, v1
	v_mov_b32_e32 v15, v1
	v_and_b32_e32 v117, 31, v6
	v_sub_u32_e32 v161, 0, v0
	v_mov_b32_e32 v0, v1
	v_mov_b32_e32 v2, v1
	v_mov_b32_e32 v3, v1
	v_mov_b32_e32 v4, v1
	v_mov_b32_e32 v5, v1
	v_mov_b32_e32 v6, v1
	v_mov_b32_e32 v7, v1
	v_mov_b32_e32 v8, v1
	v_mov_b32_e32 v9, v1
	v_mov_b32_e32 v10, v1
	v_mov_b32_e32 v11, v1
	v_mov_b32_e32 v12, v1
	v_mov_b32_e32 v13, v1
	v_mov_b64_e32 v[30:31], v[14:15]
	v_mov_b64_e32 v[46:47], v[14:15]
	s_sub_i32 s9, 0xdff, s9
	v_add_u32_e32 v156, 0xfffffe00, v126
	v_mul_u32_u24_e32 v159, 0x48, v117
	v_mov_b32_e32 v168, 0xf149f2ca
	v_mov_b32_e32 v169, 0
	v_mov_b64_e32 v[28:29], v[12:13]
	v_mov_b64_e32 v[26:27], v[10:11]
	v_mov_b64_e32 v[24:25], v[8:9]
	v_mov_b64_e32 v[22:23], v[6:7]
	v_mov_b64_e32 v[20:21], v[4:5]
	v_mov_b64_e32 v[18:19], v[2:3]
	v_mov_b64_e32 v[16:17], v[0:1]
	v_mov_b64_e32 v[44:45], v[12:13]
	v_mov_b64_e32 v[42:43], v[10:11]
	v_mov_b64_e32 v[40:41], v[8:9]
	v_mov_b64_e32 v[38:39], v[6:7]
	v_mov_b64_e32 v[36:37], v[4:5]
	v_mov_b64_e32 v[34:35], v[2:3]
	v_mov_b64_e32 v[32:33], v[0:1]
	s_mov_b32 s12, s11
	v_lshrrev_b32_e32 v218, 1, v117
	v_xor_b32_e32 v218, v218, v117
	v_and_b32_e32 v218, 4, v218
	v_lshl_add_u32 v218, v218, 1, v218
	v_xor_b32_e32 v218, v218, v117
	s_movk_i32 s4, 0x80
	v_mad_u64_u32 v[190:191], vcc, v116, s4, v[162:163]
	s_mov_b64 s[6:7], 0x800
	v_lshl_add_u64 v[190:191], v[190:191], 0, s[6:7]
	v_mov_b32_e32 v219, v202

.LBB0_307:
	s_and_b64 vcc, exec, s[4:5]
	s_cbranch_vccz .Lnsw1_edgeback
	v_mad_u32_u24 v0, v218, s37, v14
	v_lshl_add_u32 v215, v159, 1, v14
	ds_read_b128 v[220:223], v0
	ds_read_b128 v[236:239], v0 offset:4608
	ds_read_b128 v[224:227], v0 offset:32
	ds_read_b128 v[240:243], v0 offset:4640
	ds_read_b128 v[228:231], v0 offset:64
	ds_read_b128 v[244:247], v0 offset:4672
	ds_read_b128 v[232:235], v0 offset:96
	ds_read_b128 v[248:251], v0 offset:4704
	ds_read_b128 v[64:67], v215 offset:9216
	ds_read_b128 v[68:71], v215 offset:13824
	ds_read_b128 v[72:75], v215 offset:9248
	ds_read_b128 v[76:79], v215 offset:13856
	s_waitcnt lgkmcnt(11)
	v_mfma_f32_32x32x16_bf16 v[80:95], v[220:223], v[96:99], 0
	s_waitcnt lgkmcnt(10)
	v_mfma_f32_32x32x16_bf16 v[48:63], v[236:239], v[96:99], 0
	s_waitcnt lgkmcnt(9)
	v_mfma_f32_32x32x16_bf16 v[80:95], v[224:227], v[100:103], v[80:95]
	s_waitcnt lgkmcnt(8)
	v_mfma_f32_32x32x16_bf16 v[48:63], v[240:243], v[100:103], v[48:63]
	s_waitcnt lgkmcnt(7)
	v_mfma_f32_32x32x16_bf16 v[80:95], v[228:231], v[104:107], v[80:95]
	s_waitcnt lgkmcnt(6)
	v_mfma_f32_32x32x16_bf16 v[48:63], v[244:247], v[104:107], v[48:63]
	s_waitcnt lgkmcnt(5)
	v_mfma_f32_32x32x16_bf16 v[80:95], v[232:235], v[108:111], v[80:95]
	s_waitcnt lgkmcnt(4)
	v_mfma_f32_32x32x16_bf16 v[48:63], v[248:251], v[108:111], v[48:63]
	ds_read_b128 v[220:223], v215 offset:9280
	ds_read_b128 v[224:227], v215 offset:13888
	ds_read_b128 v[228:231], v215 offset:9312
	ds_read_b128 v[232:235], v215 offset:13920
	s_nop 7
	v_max3_f32 v0, v80, v81, v82
	v_max3_f32 v216, v88, v89, v90
	v_max3_f32 v0, v0, v83, v84
	v_max3_f32 v216, v216, v91, v92
	v_max3_f32 v0, v0, v85, v86
	v_max3_f32 v216, v216, v93, v94
	v_max3_f32 v0, v0, v87, v95
	v_max_f32_e32 v0, v0, v216
	ds_bpermute_b32 v216, v119, v0
	v_max3_f32 v175, v48, v49, v50
	v_max3_f32 v214, v56, v57, v58
	v_max3_f32 v175, v175, v51, v52
	v_max3_f32 v214, v214, v59, v60
	v_max3_f32 v175, v175, v53, v54
	v_max3_f32 v214, v214, v61, v62
	v_max3_f32 v175, v175, v55, v63
	v_max_f32_e32 v175, v175, v214
	ds_bpermute_b32 v214, v119, v175
	s_waitcnt lgkmcnt(1)
	v_max_f32_e32 v0, v0, v216
	v_cmp_gt_f32_e32 vcc, v0, v219
	s_cmp_eq_u64 vcc, 0
	s_cbranch_scc1 .Lnsw1_keep0
	v_max_f32_e32 v173, v168, v0
	v_sub_f32_e32 v0, v168, v173
	v_exp_f32_e32 v0, v0
	v_mov_b32_e32 v168, v173
	v_add_f32_e32 v219, 0x41200000, v173
	v_mul_f32_e32 v169, v169, v0
	v_pk_mul_f32 v[46:47], v[46:47], v[0:1] op_sel_hi:[1,0]
	v_pk_mul_f32 v[44:45], v[44:45], v[0:1] op_sel_hi:[1,0]
	v_pk_mul_f32 v[42:43], v[42:43], v[0:1] op_sel_hi:[1,0]
	v_pk_mul_f32 v[40:41], v[40:41], v[0:1] op_sel_hi:[1,0]
	v_pk_mul_f32 v[38:39], v[38:39], v[0:1] op_sel_hi:[1,0]
	v_pk_mul_f32 v[36:37], v[36:37], v[0:1] op_sel_hi:[1,0]
	v_pk_mul_f32 v[34:35], v[34:35], v[0:1] op_sel_hi:[1,0]
	v_pk_mul_f32 v[32:33], v[32:33], v[0:1] op_sel_hi:[1,0]
	v_pk_mul_f32 v[30:31], v[30:31], v[0:1] op_sel_hi:[1,0]
	v_pk_mul_f32 v[28:29], v[28:29], v[0:1] op_sel_hi:[1,0]
	v_pk_mul_f32 v[26:27], v[26:27], v[0:1] op_sel_hi:[1,0]
	v_pk_mul_f32 v[24:25], v[24:25], v[0:1] op_sel_hi:[1,0]
	v_pk_mul_f32 v[22:23], v[22:23], v[0:1] op_sel_hi:[1,0]
	v_pk_mul_f32 v[20:21], v[20:21], v[0:1] op_sel_hi:[1,0]
	v_pk_mul_f32 v[18:19], v[18:19], v[0:1] op_sel_hi:[1,0]
	v_pk_mul_f32 v[16:17], v[16:17], v[0:1] op_sel_hi:[1,0]
.Lnsw1_keep0:
	v_sub_f32_e32 v80, v80, v168
	v_exp_f32_e32 v80, v80
	v_sub_f32_e32 v81, v81, v168
	v_exp_f32_e32 v81, v81
	v_sub_f32_e32 v82, v82, v168
	v_exp_f32_e32 v82, v82
	v_add_f32_e32 v213, v81, v80
	v_sub_f32_e32 v83, v83, v168
	v_exp_f32_e32 v83, v83
	v_add_f32_e32 v213, v82, v213
	v_cvt_pk_bf16_f32 v176, v80, v81
	v_sub_f32_e32 v84, v84, v168
	v_exp_f32_e32 v84, v84
	v_add_f32_e32 v213, v83, v213
	v_sub_f32_e32 v85, v85, v168
	v_exp_f32_e32 v85, v85
	v_add_f32_e32 v213, v84, v213
	v_cvt_pk_bf16_f32 v177, v82, v83
	v_sub_f32_e32 v86, v86, v168
	v_exp_f32_e32 v86, v86
	v_add_f32_e32 v213, v85, v213
	v_sub_f32_e32 v87, v87, v168
	v_exp_f32_e32 v87, v87
	v_add_f32_e32 v213, v86, v213
	v_cvt_pk_bf16_f32 v178, v84, v85
	v_sub_f32_e32 v88, v88, v168
	v_exp_f32_e32 v88, v88
	v_add_f32_e32 v213, v87, v213
	v_sub_f32_e32 v89, v89, v168
	v_exp_f32_e32 v89, v89
	v_add_f32_e32 v213, v88, v213
	v_cvt_pk_bf16_f32 v179, v86, v87
	v_sub_f32_e32 v90, v90, v168
	v_exp_f32_e32 v90, v90
	v_add_f32_e32 v213, v89, v213
	v_mfma_f32_32x32x16_bf16 v[32:47], v[64:67], v[176:179], v[32:47]
	v_mfma_f32_32x32x16_bf16 v[16:31], v[68:71], v[176:179], v[16:31]
	v_sub_f32_e32 v91, v91, v168
	v_exp_f32_e32 v91, v91
	v_add_f32_e32 v213, v90, v213
	v_cvt_pk_bf16_f32 v180, v88, v89
	v_sub_f32_e32 v92, v92, v168
	v_exp_f32_e32 v92, v92
	v_add_f32_e32 v213, v91, v213
	v_sub_f32_e32 v93, v93, v168
	v_exp_f32_e32 v93, v93
	v_add_f32_e32 v213, v92, v213
	v_cvt_pk_bf16_f32 v181, v90, v91
	v_sub_f32_e32 v94, v94, v168
	v_exp_f32_e32 v94, v94
	v_add_f32_e32 v213, v93, v213
	v_sub_f32_e32 v95, v95, v168
	v_exp_f32_e32 v95, v95
	v_add_f32_e32 v213, v94, v213
	v_cvt_pk_bf16_f32 v182, v92, v93
	v_add_f32_e32 v213, v95, v213
	v_cvt_pk_bf16_f32 v183, v94, v95
	v_add_f32_e32 v169, v169, v213
	s_nop 0
	v_mfma_f32_32x32x16_bf16 v[32:47], v[72:75], v[180:183], v[32:47]
	v_mfma_f32_32x32x16_bf16 v[16:31], v[76:79], v[180:183], v[16:31]
	s_waitcnt lgkmcnt(0)
	v_max_f32_e32 v175, v175, v214
	v_cmp_gt_f32_e32 vcc, v175, v219
	s_cmp_eq_u64 vcc, 0
	s_cbranch_scc1 .Lnsw1_keep1
	v_max_f32_e32 v173, v168, v175
	v_sub_f32_e32 v0, v168, v173
	v_exp_f32_e32 v0, v0
	v_mov_b32_e32 v168, v173
	v_add_f32_e32 v219, 0x41200000, v173
	v_mul_f32_e32 v169, v169, v0
	v_pk_mul_f32 v[46:47], v[46:47], v[0:1] op_sel_hi:[1,0]
	v_pk_mul_f32 v[44:45], v[44:45], v[0:1] op_sel_hi:[1,0]
	v_pk_mul_f32 v[42:43], v[42:43], v[0:1] op_sel_hi:[1,0]
	v_pk_mul_f32 v[40:41], v[40:41], v[0:1] op_sel_hi:[1,0]
	v_pk_mul_f32 v[38:39], v[38:39], v[0:1] op_sel_hi:[1,0]
	v_pk_mul_f32 v[36:37], v[36:37], v[0:1] op_sel_hi:[1,0]
	v_pk_mul_f32 v[34:35], v[34:35], v[0:1] op_sel_hi:[1,0]
	v_pk_mul_f32 v[32:33], v[32:33], v[0:1] op_sel_hi:[1,0]
	v_pk_mul_f32 v[30:31], v[30:31], v[0:1] op_sel_hi:[1,0]
	v_pk_mul_f32 v[28:29], v[28:29], v[0:1] op_sel_hi:[1,0]
	v_pk_mul_f32 v[26:27], v[26:27], v[0:1] op_sel_hi:[1,0]
	v_pk_mul_f32 v[24:25], v[24:25], v[0:1] op_sel_hi:[1,0]
	v_pk_mul_f32 v[22:23], v[22:23], v[0:1] op_sel_hi:[1,0]
	v_pk_mul_f32 v[20:21], v[20:21], v[0:1] op_sel_hi:[1,0]
	v_pk_mul_f32 v[18:19], v[18:19], v[0:1] op_sel_hi:[1,0]
	v_pk_mul_f32 v[16:17], v[16:17], v[0:1] op_sel_hi:[1,0]
.Lnsw1_keep1:
	v_sub_f32_e32 v48, v48, v168
	v_exp_f32_e32 v48, v48
	v_sub_f32_e32 v49, v49, v168
	v_exp_f32_e32 v49, v49
	v_sub_f32_e32 v50, v50, v168
	v_exp_f32_e32 v50, v50
	v_add_f32_e32 v213, v49, v48
	v_sub_f32_e32 v51, v51, v168
	v_exp_f32_e32 v51, v51
	v_add_f32_e32 v213, v50, v213
	v_cvt_pk_bf16_f32 v80, v48, v49
	v_sub_f32_e32 v52, v52, v168
	v_exp_f32_e32 v52, v52
	v_add_f32_e32 v213, v51, v213
	v_sub_f32_e32 v53, v53, v168
	v_exp_f32_e32 v53, v53
	v_add_f32_e32 v213, v52, v213
	v_cvt_pk_bf16_f32 v81, v50, v51
	v_sub_f32_e32 v54, v54, v168
	v_exp_f32_e32 v54, v54
	v_add_f32_e32 v213, v53, v213
	v_sub_f32_e32 v55, v55, v168
	v_exp_f32_e32 v55, v55
	v_add_f32_e32 v213, v54, v213
	v_cvt_pk_bf16_f32 v82, v52, v53
	v_sub_f32_e32 v56, v56, v168
	v_exp_f32_e32 v56, v56
	v_add_f32_e32 v213, v55, v213
	v_sub_f32_e32 v57, v57, v168
	v_exp_f32_e32 v57, v57
	v_add_f32_e32 v213, v56, v213
	v_cvt_pk_bf16_f32 v83, v54, v55
	v_sub_f32_e32 v58, v58, v168
	v_exp_f32_e32 v58, v58
	v_add_f32_e32 v213, v57, v213
	v_mfma_f32_32x32x16_bf16 v[32:47], v[220:223], v[80:83], v[32:47]
	v_mfma_f32_32x32x16_bf16 v[16:31], v[224:227], v[80:83], v[16:31]
	v_sub_f32_e32 v59, v59, v168
	v_exp_f32_e32 v59, v59
	v_add_f32_e32 v213, v58, v213
	v_cvt_pk_bf16_f32 v84, v56, v57
	v_sub_f32_e32 v60, v60, v168
	v_exp_f32_e32 v60, v60
	v_add_f32_e32 v213, v59, v213
	v_sub_f32_e32 v61, v61, v168
	v_exp_f32_e32 v61, v61
	v_add_f32_e32 v213, v60, v213
	v_cvt_pk_bf16_f32 v85, v58, v59
	v_sub_f32_e32 v62, v62, v168
	v_exp_f32_e32 v62, v62
	v_add_f32_e32 v213, v61, v213
	v_sub_f32_e32 v63, v63, v168
	v_exp_f32_e32 v63, v63
	v_add_f32_e32 v213, v62, v213
	v_cvt_pk_bf16_f32 v86, v60, v61
	v_add_f32_e32 v213, v63, v213
	v_cvt_pk_bf16_f32 v87, v62, v63
	v_add_f32_e32 v169, v169, v213
	s_nop 0
	v_mfma_f32_32x32x16_bf16 v[32:47], v[228:231], v[84:87], v[32:47]
	v_mfma_f32_32x32x16_bf16 v[16:31], v[232:235], v[84:87], v[16:31]
	s_branch .LBB0_314
